# speedup vs baseline: 1.0297x; 1.0297x over previous
.Lgio_entry:
	v_readlane_b32 s0, v236, 0
	s_cmpk_lg_u32 s0, 0x200
	s_cbranch_scc1 .LBB0_442
	v_lshrrev_b32_e32 v90, 3, v93
	v_and_b32_e32 v195, 7, v93
	v_bfe_u32 v232, v90, 1, 3
	v_xor_b32_e32 v195, v195, v232
	v_lshlrev_b32_e32 v195, 4, v195
	v_lshl_or_b32 v166, v90, 12, v195
	v_add_u32_e32 v167, 0x20000, v166
	v_add_u32_e32 v168, 0x40000, v166
	v_add_u32_e32 v169, 0x60000, v166
	v_and_b32_e32 v232, 12, v90
	v_lshlrev_b32_e32 v232, 1, v232
	v_and_or_b32 v232, v90, 3, v232
	v_lshrrev_b32_e32 v90, 4, v90
	v_lshl_or_b32 v232, v90, 2, v232
	v_lshl_or_b32 v170, v232, 12, v195
	v_add_u32_e32 v171, 0x20000, v170
	v_add_u32_e32 v172, 0x40000, v170
	v_add_u32_e32 v173, 0x60000, v170
	v_lshrrev_b32_e32 v90, 6, v93
	v_and_b32_e32 v195, 15, v93
	v_readfirstlane_b32 s17, v90
	v_bfe_u32 v232, v93, 4, 2
	s_lshl_b32 s14, s17, 10
	s_lshr_b32 s20, s17, 1
	s_and_b32 s21, s17, 1
	s_lshl_b32 s20, s20, 6
	s_lshl_b32 s21, s21, 6
	v_bfe_u32 v90, v195, 1, 3
	v_xor_b32_e32 v90, v90, v232
	v_lshlrev_b32_e32 v90, 4, v90
	v_add_u32_e32 v229, s20, v195
	v_add_u32_e32 v231, s21, v195
	v_lshl_or_b32 v228, v229, 7, v90
	v_lshl_or_b32 v230, v231, 7, v90
	v_lshl_add_u32 v232, v232, 3, s21
	v_lshlrev_b32_e32 v232, 1, v232
	v_lshl_or_b32 v89, v229, 14, v232
	v_xor_b32_e32 v229, 64, v228
	v_xor_b32_e32 v231, 64, v230
	s_and_b32 s0, s2, 1
	s_lshl_b32 s0, s0, 3
	s_bfe_u32 s1, s2, 0x30003
	s_or_b32 s20, s0, s1
	s_bfe_u32 s0, s2, 0x20001
	s_lshl_b32 s0, s0, 3
	s_lshr_b32 s1, s2, 6
	s_or_b32 s21, s0, s1
	v_readlane_b32 s4, v236, 51
	v_readlane_b32 s5, v236, 52
	v_readlane_b32 s6, v236, 55
	v_readlane_b32 s7, v236, 56
	v_readlane_b32 s10, v236, 53
	v_readlane_b32 s11, v236, 54
	s_lshl_b32 s0, s20, 19
	s_add_u32 s4, s4, s0
	s_addc_u32 s5, s5, 0
	s_lshl_b32 s0, s21, 19
	s_add_u32 s6, s6, s0
	s_addc_u32 s7, s7, 0
	s_add_u32 s8, s6, 0x1000000
	s_addc_u32 s9, s7, 0
	s_lshl_b32 s0, s20, 21
	s_add_u32 s10, s10, s0
	s_addc_u32 s11, s11, 0
	s_lshl_b32 s0, s21, 8
	s_add_u32 s10, s10, s0
	s_addc_u32 s11, s11, 0
	s_add_u32 s12, s10, 0x2000
	s_addc_u32 s13, s11, 0
	s_movk_i32 s16, 18
	s_add_i32 m0, s14, 0x0
	s_nop 0
	global_load_lds_dwordx4 v166, s[4:5]
	s_add_i32 m0, s14, 0x1000
	s_nop 0
	global_load_lds_dwordx4 v167, s[4:5]
	s_add_i32 m0, s14, 0x2000
	s_nop 0
	global_load_lds_dwordx4 v168, s[4:5]
	s_add_i32 m0, s14, 0x3000
	s_nop 0
	global_load_lds_dwordx4 v169, s[4:5]
	s_add_i32 m0, s14, 0x4000
	s_nop 0
	global_load_lds_dwordx4 v170, s[8:9]
	s_add_i32 m0, s14, 0x5000
	s_nop 0
	global_load_lds_dwordx4 v171, s[8:9]
	s_add_i32 m0, s14, 0x6000
	s_nop 0
	global_load_lds_dwordx4 v172, s[8:9]
	s_add_i32 m0, s14, 0x7000
	s_nop 0
	global_load_lds_dwordx4 v173, s[8:9]
	s_add_i32 m0, s14, 0x8000
	s_nop 0
	global_load_lds_dwordx4 v170, s[6:7]
	s_add_i32 m0, s14, 0x9000
	s_nop 0
	global_load_lds_dwordx4 v171, s[6:7]
	s_add_i32 m0, s14, 0xa000
	s_nop 0
	global_load_lds_dwordx4 v172, s[6:7]
	s_add_i32 m0, s14, 0xb000
	s_nop 0
	global_load_lds_dwordx4 v173, s[6:7]
	v_add_u32_e32 v166, 0x80, v166
	v_add_u32_e32 v167, 0x80, v167
	v_add_u32_e32 v168, 0x80, v168
	v_add_u32_e32 v169, 0x80, v169
	v_add_u32_e32 v170, 0x80, v170
	v_add_u32_e32 v171, 0x80, v171
	v_add_u32_e32 v172, 0x80, v172
	v_add_u32_e32 v173, 0x80, v173
.Lgio_tile:
	v_mov_b32_e32 v0, 0
	v_mov_b32_e32 v1, 0
	v_mov_b32_e32 v2, 0
	v_mov_b32_e32 v3, 0
	v_mov_b32_e32 v4, 0
	v_mov_b32_e32 v5, 0
	v_mov_b32_e32 v6, 0
	v_mov_b32_e32 v7, 0
	v_mov_b32_e32 v8, 0
	v_mov_b32_e32 v9, 0
	v_mov_b32_e32 v10, 0
	v_mov_b32_e32 v11, 0
	v_mov_b32_e32 v12, 0
	v_mov_b32_e32 v13, 0
	v_mov_b32_e32 v14, 0
	v_mov_b32_e32 v15, 0
	v_mov_b32_e32 v16, 0
	v_mov_b32_e32 v17, 0
	v_mov_b32_e32 v18, 0
	v_mov_b32_e32 v19, 0
	v_mov_b32_e32 v20, 0
	v_mov_b32_e32 v21, 0
	v_mov_b32_e32 v22, 0
	v_mov_b32_e32 v23, 0
	v_mov_b32_e32 v24, 0
	v_mov_b32_e32 v25, 0
	v_mov_b32_e32 v26, 0
	v_mov_b32_e32 v27, 0
	v_mov_b32_e32 v28, 0
	v_mov_b32_e32 v29, 0
	v_mov_b32_e32 v30, 0
	v_mov_b32_e32 v31, 0
	v_mov_b32_e32 v32, 0
	v_mov_b32_e32 v33, 0
	v_mov_b32_e32 v34, 0
	v_mov_b32_e32 v35, 0
	v_mov_b32_e32 v36, 0
	v_mov_b32_e32 v37, 0
	v_mov_b32_e32 v38, 0
	v_mov_b32_e32 v39, 0
	v_mov_b32_e32 v40, 0
	v_mov_b32_e32 v41, 0
	v_mov_b32_e32 v42, 0
	v_mov_b32_e32 v43, 0
	v_mov_b32_e32 v44, 0
	v_mov_b32_e32 v45, 0
	v_mov_b32_e32 v46, 0
	v_mov_b32_e32 v47, 0
	v_mov_b32_e32 v48, 0
	v_mov_b32_e32 v49, 0
	v_mov_b32_e32 v50, 0
	v_mov_b32_e32 v51, 0
	v_mov_b32_e32 v52, 0
	v_mov_b32_e32 v53, 0
	v_mov_b32_e32 v54, 0
	v_mov_b32_e32 v55, 0
	v_mov_b32_e32 v56, 0
	v_mov_b32_e32 v57, 0
	v_mov_b32_e32 v58, 0
	v_mov_b32_e32 v59, 0
	v_mov_b32_e32 v60, 0
	v_mov_b32_e32 v61, 0
	v_mov_b32_e32 v62, 0
	v_mov_b32_e32 v63, 0
	v_mov_b32_e32 v94, 0
	v_mov_b32_e32 v95, 0
	v_mov_b32_e32 v96, 0
	v_mov_b32_e32 v97, 0
	v_mov_b32_e32 v98, 0
	v_mov_b32_e32 v99, 0
	v_mov_b32_e32 v100, 0
	v_mov_b32_e32 v101, 0
	v_mov_b32_e32 v102, 0
	v_mov_b32_e32 v103, 0
	v_mov_b32_e32 v104, 0
	v_mov_b32_e32 v105, 0
	v_mov_b32_e32 v106, 0
	v_mov_b32_e32 v107, 0
	v_mov_b32_e32 v108, 0
	v_mov_b32_e32 v109, 0
	v_mov_b32_e32 v110, 0
	v_mov_b32_e32 v111, 0
	v_mov_b32_e32 v112, 0
	v_mov_b32_e32 v113, 0
	v_mov_b32_e32 v114, 0
	v_mov_b32_e32 v115, 0
	v_mov_b32_e32 v116, 0
	v_mov_b32_e32 v117, 0
	v_mov_b32_e32 v118, 0
	v_mov_b32_e32 v119, 0
	v_mov_b32_e32 v120, 0
	v_mov_b32_e32 v121, 0
	v_mov_b32_e32 v122, 0
	v_mov_b32_e32 v123, 0
	v_mov_b32_e32 v124, 0
	v_mov_b32_e32 v125, 0
	v_mov_b32_e32 v126, 0
	v_mov_b32_e32 v127, 0
	v_mov_b32_e32 v128, 0
	v_mov_b32_e32 v129, 0
	v_mov_b32_e32 v130, 0
	v_mov_b32_e32 v131, 0
	v_mov_b32_e32 v132, 0
	v_mov_b32_e32 v133, 0
	v_mov_b32_e32 v134, 0
	v_mov_b32_e32 v135, 0
	v_mov_b32_e32 v136, 0
	v_mov_b32_e32 v137, 0
	v_mov_b32_e32 v138, 0
	v_mov_b32_e32 v139, 0
	v_mov_b32_e32 v140, 0
	v_mov_b32_e32 v141, 0
	v_mov_b32_e32 v142, 0
	v_mov_b32_e32 v143, 0
	v_mov_b32_e32 v144, 0
	v_mov_b32_e32 v145, 0
	v_mov_b32_e32 v146, 0
	v_mov_b32_e32 v147, 0
	v_mov_b32_e32 v148, 0
	v_mov_b32_e32 v149, 0
	v_mov_b32_e32 v150, 0
	v_mov_b32_e32 v151, 0
	v_mov_b32_e32 v152, 0
	v_mov_b32_e32 v153, 0
	v_mov_b32_e32 v154, 0
	v_mov_b32_e32 v155, 0
	v_mov_b32_e32 v156, 0
	v_mov_b32_e32 v157, 0
	s_movk_i32 s15, 16
.Lgio_k:
	s_waitcnt vmcnt(0)
	s_barrier
	ds_read_b128 v[196:199], v228 offset:0
	ds_read_b128 v[200:203], v228 offset:2048
	ds_read_b128 v[204:207], v228 offset:4096
	ds_read_b128 v[208:211], v228 offset:6144
	ds_read_b128 v[212:215], v229 offset:0
	ds_read_b128 v[216:219], v229 offset:2048
	ds_read_b128 v[220:223], v229 offset:4096
	ds_read_b128 v[224:227], v229 offset:6144
	ds_read_b128 v[64:67], v230 offset:16384
	ds_read_b128 v[68:71], v230 offset:18432
	ds_read_b128 v[72:75], v230 offset:20480
	ds_read_b128 v[76:79], v230 offset:22528
	ds_read_b128 v[80:83], v231 offset:16384
	ds_read_b128 v[84:87], v231 offset:18432
	ds_read_b128 v[158:161], v231 offset:20480
	ds_read_b128 v[162:165], v231 offset:22528
	s_waitcnt lgkmcnt(0)
	s_barrier
	s_setprio 1
	s_add_i32 m0, s14, 0x0
	v_mfma_f32_16x16x32_bf16 v[94:97], v[64:67], v[196:199], v[94:97]
	global_load_lds_dwordx4 v166, s[4:5]
	v_mfma_f32_16x16x32_bf16 v[110:113], v[64:67], v[200:203], v[110:113]
	s_add_i32 m0, s14, 0x1000
	v_mfma_f32_16x16x32_bf16 v[126:129], v[64:67], v[204:207], v[126:129]
	global_load_lds_dwordx4 v167, s[4:5]
	v_mfma_f32_16x16x32_bf16 v[142:145], v[64:67], v[208:211], v[142:145]
	ds_read_b128 v[64:67], v230 offset:32768
	s_add_i32 m0, s14, 0x2000
	v_mfma_f32_16x16x32_bf16 v[98:101], v[68:71], v[196:199], v[98:101]
	global_load_lds_dwordx4 v168, s[4:5]
	v_mfma_f32_16x16x32_bf16 v[114:117], v[68:71], v[200:203], v[114:117]
	s_add_i32 m0, s14, 0x3000
	v_mfma_f32_16x16x32_bf16 v[130:133], v[68:71], v[204:207], v[130:133]
	global_load_lds_dwordx4 v169, s[4:5]
	v_mfma_f32_16x16x32_bf16 v[146:149], v[68:71], v[208:211], v[146:149]
	ds_read_b128 v[68:71], v230 offset:34816
	s_add_i32 m0, s14, 0x4000
	v_mfma_f32_16x16x32_bf16 v[102:105], v[72:75], v[196:199], v[102:105]
	global_load_lds_dwordx4 v170, s[8:9]
	v_mfma_f32_16x16x32_bf16 v[118:121], v[72:75], v[200:203], v[118:121]
	s_add_i32 m0, s14, 0x5000
	v_mfma_f32_16x16x32_bf16 v[134:137], v[72:75], v[204:207], v[134:137]
	global_load_lds_dwordx4 v171, s[8:9]
	v_mfma_f32_16x16x32_bf16 v[150:153], v[72:75], v[208:211], v[150:153]
	ds_read_b128 v[72:75], v230 offset:36864
	s_add_i32 m0, s14, 0x6000
	v_mfma_f32_16x16x32_bf16 v[106:109], v[76:79], v[196:199], v[106:109]
	global_load_lds_dwordx4 v172, s[8:9]
	v_mfma_f32_16x16x32_bf16 v[122:125], v[76:79], v[200:203], v[122:125]
	s_add_i32 m0, s14, 0x7000
	v_mfma_f32_16x16x32_bf16 v[138:141], v[76:79], v[204:207], v[138:141]
	global_load_lds_dwordx4 v173, s[8:9]
	v_mfma_f32_16x16x32_bf16 v[154:157], v[76:79], v[208:211], v[154:157]
	ds_read_b128 v[76:79], v230 offset:38912
	s_add_i32 m0, s14, 0xc000
	v_mfma_f32_16x16x32_bf16 v[94:97], v[80:83], v[212:215], v[94:97]
	global_load_lds_dwordx4 v170, s[6:7]
	v_mfma_f32_16x16x32_bf16 v[110:113], v[80:83], v[216:219], v[110:113]
	s_add_i32 m0, s14, 0xd000
	v_mfma_f32_16x16x32_bf16 v[126:129], v[80:83], v[220:223], v[126:129]
	global_load_lds_dwordx4 v171, s[6:7]
	v_mfma_f32_16x16x32_bf16 v[142:145], v[80:83], v[224:227], v[142:145]
	ds_read_b128 v[80:83], v231 offset:32768
	s_add_i32 m0, s14, 0xe000
	v_mfma_f32_16x16x32_bf16 v[98:101], v[84:87], v[212:215], v[98:101]
	global_load_lds_dwordx4 v172, s[6:7]
	v_mfma_f32_16x16x32_bf16 v[114:117], v[84:87], v[216:219], v[114:117]
	s_add_i32 m0, s14, 0xf000
	v_mfma_f32_16x16x32_bf16 v[130:133], v[84:87], v[220:223], v[130:133]
	global_load_lds_dwordx4 v173, s[6:7]
	v_mfma_f32_16x16x32_bf16 v[146:149], v[84:87], v[224:227], v[146:149]
	ds_read_b128 v[84:87], v231 offset:34816
	v_mfma_f32_16x16x32_bf16 v[102:105], v[158:161], v[212:215], v[102:105]
	v_add_u32_e32 v166, 0x80, v166
	v_mfma_f32_16x16x32_bf16 v[118:121], v[158:161], v[216:219], v[118:121]
	v_add_u32_e32 v167, 0x80, v167
	v_mfma_f32_16x16x32_bf16 v[134:137], v[158:161], v[220:223], v[134:137]
	v_add_u32_e32 v168, 0x80, v168
	v_mfma_f32_16x16x32_bf16 v[150:153], v[158:161], v[224:227], v[150:153]
	v_add_u32_e32 v169, 0x80, v169
	ds_read_b128 v[158:161], v231 offset:36864
	v_mfma_f32_16x16x32_bf16 v[106:109], v[162:165], v[212:215], v[106:109]
	v_add_u32_e32 v170, 0x80, v170
	v_mfma_f32_16x16x32_bf16 v[122:125], v[162:165], v[216:219], v[122:125]
	v_add_u32_e32 v171, 0x80, v171
	v_mfma_f32_16x16x32_bf16 v[138:141], v[162:165], v[220:223], v[138:141]
	v_add_u32_e32 v172, 0x80, v172
	v_mfma_f32_16x16x32_bf16 v[154:157], v[162:165], v[224:227], v[154:157]
	v_add_u32_e32 v173, 0x80, v173
	ds_read_b128 v[162:165], v231 offset:38912
	s_waitcnt lgkmcnt(7)
	v_mfma_f32_16x16x32_bf16 v[0:3], v[64:67], v[196:199], v[0:3]
	v_mfma_f32_16x16x32_bf16 v[16:19], v[64:67], v[200:203], v[16:19]
	v_mfma_f32_16x16x32_bf16 v[32:35], v[64:67], v[204:207], v[32:35]
	v_mfma_f32_16x16x32_bf16 v[48:51], v[64:67], v[208:211], v[48:51]
	s_waitcnt lgkmcnt(6)
	v_mfma_f32_16x16x32_bf16 v[4:7], v[68:71], v[196:199], v[4:7]
	v_mfma_f32_16x16x32_bf16 v[20:23], v[68:71], v[200:203], v[20:23]
	v_mfma_f32_16x16x32_bf16 v[36:39], v[68:71], v[204:207], v[36:39]
	v_mfma_f32_16x16x32_bf16 v[52:55], v[68:71], v[208:211], v[52:55]
	s_waitcnt lgkmcnt(5)
	v_mfma_f32_16x16x32_bf16 v[8:11], v[72:75], v[196:199], v[8:11]
	v_mfma_f32_16x16x32_bf16 v[24:27], v[72:75], v[200:203], v[24:27]
	v_mfma_f32_16x16x32_bf16 v[40:43], v[72:75], v[204:207], v[40:43]
	v_mfma_f32_16x16x32_bf16 v[56:59], v[72:75], v[208:211], v[56:59]
	s_waitcnt lgkmcnt(4)
	v_mfma_f32_16x16x32_bf16 v[12:15], v[76:79], v[196:199], v[12:15]
	v_mfma_f32_16x16x32_bf16 v[28:31], v[76:79], v[200:203], v[28:31]
	v_mfma_f32_16x16x32_bf16 v[44:47], v[76:79], v[204:207], v[44:47]
	v_mfma_f32_16x16x32_bf16 v[60:63], v[76:79], v[208:211], v[60:63]
	s_waitcnt lgkmcnt(3)
	v_mfma_f32_16x16x32_bf16 v[0:3], v[80:83], v[212:215], v[0:3]
	v_mfma_f32_16x16x32_bf16 v[16:19], v[80:83], v[216:219], v[16:19]
	v_mfma_f32_16x16x32_bf16 v[32:35], v[80:83], v[220:223], v[32:35]
	v_mfma_f32_16x16x32_bf16 v[48:51], v[80:83], v[224:227], v[48:51]
	s_waitcnt lgkmcnt(2)
	v_mfma_f32_16x16x32_bf16 v[4:7], v[84:87], v[212:215], v[4:7]
	v_mfma_f32_16x16x32_bf16 v[20:23], v[84:87], v[216:219], v[20:23]
	v_mfma_f32_16x16x32_bf16 v[36:39], v[84:87], v[220:223], v[36:39]
	v_mfma_f32_16x16x32_bf16 v[52:55], v[84:87], v[224:227], v[52:55]
	s_waitcnt lgkmcnt(1)
	v_mfma_f32_16x16x32_bf16 v[8:11], v[158:161], v[212:215], v[8:11]
	v_mfma_f32_16x16x32_bf16 v[24:27], v[158:161], v[216:219], v[24:27]
	v_mfma_f32_16x16x32_bf16 v[40:43], v[158:161], v[220:223], v[40:43]
	v_mfma_f32_16x16x32_bf16 v[56:59], v[158:161], v[224:227], v[56:59]
	s_waitcnt lgkmcnt(0)
	v_mfma_f32_16x16x32_bf16 v[12:15], v[162:165], v[212:215], v[12:15]
	v_mfma_f32_16x16x32_bf16 v[28:31], v[162:165], v[216:219], v[28:31]
	v_mfma_f32_16x16x32_bf16 v[44:47], v[162:165], v[220:223], v[44:47]
	v_mfma_f32_16x16x32_bf16 v[60:63], v[162:165], v[224:227], v[60:63]
	s_setprio 0
	s_waitcnt vmcnt(0)
	s_barrier
	ds_read_b128 v[196:199], v228 offset:0
	ds_read_b128 v[200:203], v228 offset:2048
	ds_read_b128 v[204:207], v228 offset:4096
	ds_read_b128 v[208:211], v228 offset:6144
	ds_read_b128 v[212:215], v229 offset:0
	ds_read_b128 v[216:219], v229 offset:2048
	ds_read_b128 v[220:223], v229 offset:4096
	ds_read_b128 v[224:227], v229 offset:6144
	ds_read_b128 v[64:67], v230 offset:16384
	ds_read_b128 v[68:71], v230 offset:18432
	ds_read_b128 v[72:75], v230 offset:20480
	ds_read_b128 v[76:79], v230 offset:22528
	ds_read_b128 v[80:83], v231 offset:16384
	ds_read_b128 v[84:87], v231 offset:18432
	ds_read_b128 v[158:161], v231 offset:20480
	ds_read_b128 v[162:165], v231 offset:22528
	s_cmp_eq_u32 s15, 1
	s_cselect_b32 s0, 0xfffff000, 0
	s_cselect_b32 s1, -1, 0
	s_cselect_b32 s22, 0x800000, 0
	s_cmp_eq_u32 s16, 1
	s_cselect_b32 s22, 0, s22
	s_add_u32 s6, s6, s0
	s_addc_u32 s7, s7, s1
	s_add_u32 s8, s8, s0
	s_addc_u32 s9, s9, s1
	s_add_u32 s4, s4, s0
	s_addc_u32 s5, s5, s1
	s_add_u32 s4, s4, s22
	s_addc_u32 s5, s5, 0
	s_waitcnt lgkmcnt(0)
	s_barrier
	s_setprio 1
	s_add_i32 m0, s14, 0x0
	v_mfma_f32_16x16x32_bf16 v[94:97], v[64:67], v[196:199], v[94:97]
	global_load_lds_dwordx4 v166, s[4:5]
	v_mfma_f32_16x16x32_bf16 v[110:113], v[64:67], v[200:203], v[110:113]
	s_add_i32 m0, s14, 0x1000
	v_mfma_f32_16x16x32_bf16 v[126:129], v[64:67], v[204:207], v[126:129]
	global_load_lds_dwordx4 v167, s[4:5]
	v_mfma_f32_16x16x32_bf16 v[142:145], v[64:67], v[208:211], v[142:145]
	ds_read_b128 v[64:67], v230 offset:49152
	s_add_i32 m0, s14, 0x2000
	v_mfma_f32_16x16x32_bf16 v[98:101], v[68:71], v[196:199], v[98:101]
	global_load_lds_dwordx4 v168, s[4:5]
	v_mfma_f32_16x16x32_bf16 v[114:117], v[68:71], v[200:203], v[114:117]
	s_add_i32 m0, s14, 0x3000
	v_mfma_f32_16x16x32_bf16 v[130:133], v[68:71], v[204:207], v[130:133]
	global_load_lds_dwordx4 v169, s[4:5]
	v_mfma_f32_16x16x32_bf16 v[146:149], v[68:71], v[208:211], v[146:149]
	ds_read_b128 v[68:71], v230 offset:51200
	s_add_i32 m0, s14, 0x4000
	v_mfma_f32_16x16x32_bf16 v[102:105], v[72:75], v[196:199], v[102:105]
	global_load_lds_dwordx4 v170, s[8:9]
	v_mfma_f32_16x16x32_bf16 v[118:121], v[72:75], v[200:203], v[118:121]
	s_add_i32 m0, s14, 0x5000
	v_mfma_f32_16x16x32_bf16 v[134:137], v[72:75], v[204:207], v[134:137]
	global_load_lds_dwordx4 v171, s[8:9]
	v_mfma_f32_16x16x32_bf16 v[150:153], v[72:75], v[208:211], v[150:153]
	ds_read_b128 v[72:75], v230 offset:53248
	s_add_i32 m0, s14, 0x6000
	v_mfma_f32_16x16x32_bf16 v[106:109], v[76:79], v[196:199], v[106:109]
	global_load_lds_dwordx4 v172, s[8:9]
	v_mfma_f32_16x16x32_bf16 v[122:125], v[76:79], v[200:203], v[122:125]
	s_add_i32 m0, s14, 0x7000
	v_mfma_f32_16x16x32_bf16 v[138:141], v[76:79], v[204:207], v[138:141]
	global_load_lds_dwordx4 v173, s[8:9]
	v_mfma_f32_16x16x32_bf16 v[154:157], v[76:79], v[208:211], v[154:157]
	ds_read_b128 v[76:79], v230 offset:55296
	s_add_i32 m0, s14, 0x8000
	v_mfma_f32_16x16x32_bf16 v[94:97], v[80:83], v[212:215], v[94:97]
	global_load_lds_dwordx4 v170, s[6:7]
	v_mfma_f32_16x16x32_bf16 v[110:113], v[80:83], v[216:219], v[110:113]
	s_add_i32 m0, s14, 0x9000
	v_mfma_f32_16x16x32_bf16 v[126:129], v[80:83], v[220:223], v[126:129]
	global_load_lds_dwordx4 v171, s[6:7]
	v_mfma_f32_16x16x32_bf16 v[142:145], v[80:83], v[224:227], v[142:145]
	ds_read_b128 v[80:83], v231 offset:49152
	s_add_i32 m0, s14, 0xa000
	v_mfma_f32_16x16x32_bf16 v[98:101], v[84:87], v[212:215], v[98:101]
	global_load_lds_dwordx4 v172, s[6:7]
	v_mfma_f32_16x16x32_bf16 v[114:117], v[84:87], v[216:219], v[114:117]
	s_add_i32 m0, s14, 0xb000
	v_mfma_f32_16x16x32_bf16 v[130:133], v[84:87], v[220:223], v[130:133]
	global_load_lds_dwordx4 v173, s[6:7]
	v_mfma_f32_16x16x32_bf16 v[146:149], v[84:87], v[224:227], v[146:149]
	ds_read_b128 v[84:87], v231 offset:51200
	v_mfma_f32_16x16x32_bf16 v[102:105], v[158:161], v[212:215], v[102:105]
	v_add_u32_e32 v166, 0x80, v166
	v_mfma_f32_16x16x32_bf16 v[118:121], v[158:161], v[216:219], v[118:121]
	v_add_u32_e32 v167, 0x80, v167
	v_mfma_f32_16x16x32_bf16 v[134:137], v[158:161], v[220:223], v[134:137]
	v_add_u32_e32 v168, 0x80, v168
	v_mfma_f32_16x16x32_bf16 v[150:153], v[158:161], v[224:227], v[150:153]
	v_add_u32_e32 v169, 0x80, v169
	ds_read_b128 v[158:161], v231 offset:53248
	v_mfma_f32_16x16x32_bf16 v[106:109], v[162:165], v[212:215], v[106:109]
	v_add_u32_e32 v170, 0x80, v170
	v_mfma_f32_16x16x32_bf16 v[122:125], v[162:165], v[216:219], v[122:125]
	v_add_u32_e32 v171, 0x80, v171
	v_mfma_f32_16x16x32_bf16 v[138:141], v[162:165], v[220:223], v[138:141]
	v_add_u32_e32 v172, 0x80, v172
	v_mfma_f32_16x16x32_bf16 v[154:157], v[162:165], v[224:227], v[154:157]
	v_add_u32_e32 v173, 0x80, v173
	ds_read_b128 v[162:165], v231 offset:55296
	s_waitcnt lgkmcnt(7)
	v_mfma_f32_16x16x32_bf16 v[0:3], v[64:67], v[196:199], v[0:3]
	v_mfma_f32_16x16x32_bf16 v[16:19], v[64:67], v[200:203], v[16:19]
	v_mfma_f32_16x16x32_bf16 v[32:35], v[64:67], v[204:207], v[32:35]
	v_mfma_f32_16x16x32_bf16 v[48:51], v[64:67], v[208:211], v[48:51]
	s_waitcnt lgkmcnt(6)
	v_mfma_f32_16x16x32_bf16 v[4:7], v[68:71], v[196:199], v[4:7]
	v_mfma_f32_16x16x32_bf16 v[20:23], v[68:71], v[200:203], v[20:23]
	v_mfma_f32_16x16x32_bf16 v[36:39], v[68:71], v[204:207], v[36:39]
	v_mfma_f32_16x16x32_bf16 v[52:55], v[68:71], v[208:211], v[52:55]
	s_waitcnt lgkmcnt(5)
	v_mfma_f32_16x16x32_bf16 v[8:11], v[72:75], v[196:199], v[8:11]
	v_mfma_f32_16x16x32_bf16 v[24:27], v[72:75], v[200:203], v[24:27]
	v_mfma_f32_16x16x32_bf16 v[40:43], v[72:75], v[204:207], v[40:43]
	v_mfma_f32_16x16x32_bf16 v[56:59], v[72:75], v[208:211], v[56:59]
	s_waitcnt lgkmcnt(4)
	v_mfma_f32_16x16x32_bf16 v[12:15], v[76:79], v[196:199], v[12:15]
	v_mfma_f32_16x16x32_bf16 v[28:31], v[76:79], v[200:203], v[28:31]
	v_mfma_f32_16x16x32_bf16 v[44:47], v[76:79], v[204:207], v[44:47]
	v_mfma_f32_16x16x32_bf16 v[60:63], v[76:79], v[208:211], v[60:63]
	s_waitcnt lgkmcnt(3)
	v_mfma_f32_16x16x32_bf16 v[0:3], v[80:83], v[212:215], v[0:3]
	v_mfma_f32_16x16x32_bf16 v[16:19], v[80:83], v[216:219], v[16:19]
	v_mfma_f32_16x16x32_bf16 v[32:35], v[80:83], v[220:223], v[32:35]
	v_mfma_f32_16x16x32_bf16 v[48:51], v[80:83], v[224:227], v[48:51]
	s_waitcnt lgkmcnt(2)
	v_mfma_f32_16x16x32_bf16 v[4:7], v[84:87], v[212:215], v[4:7]
	v_mfma_f32_16x16x32_bf16 v[20:23], v[84:87], v[216:219], v[20:23]
	v_mfma_f32_16x16x32_bf16 v[36:39], v[84:87], v[220:223], v[36:39]
	v_mfma_f32_16x16x32_bf16 v[52:55], v[84:87], v[224:227], v[52:55]
	s_waitcnt lgkmcnt(1)
	v_mfma_f32_16x16x32_bf16 v[8:11], v[158:161], v[212:215], v[8:11]
	v_mfma_f32_16x16x32_bf16 v[24:27], v[158:161], v[216:219], v[24:27]
	v_mfma_f32_16x16x32_bf16 v[40:43], v[158:161], v[220:223], v[40:43]
	v_mfma_f32_16x16x32_bf16 v[56:59], v[158:161], v[224:227], v[56:59]
	s_waitcnt lgkmcnt(0)
	v_mfma_f32_16x16x32_bf16 v[12:15], v[162:165], v[212:215], v[12:15]
	v_mfma_f32_16x16x32_bf16 v[28:31], v[162:165], v[216:219], v[28:31]
	v_mfma_f32_16x16x32_bf16 v[44:47], v[162:165], v[220:223], v[44:47]
	v_mfma_f32_16x16x32_bf16 v[60:63], v[162:165], v[224:227], v[60:63]
	s_setprio 0
	s_add_i32 s15, s15, -1
	s_cmp_lg_u32 s15, 0
	s_cbranch_scc1 .Lgio_k
	s_nop 7
	s_add_u32 s0, s10, 0x0
	s_addc_u32 s1, s11, 0
	v_cvt_pk_bf16_f32 v196, v0, v1
	v_cvt_pk_bf16_f32 v197, v2, v3
	v_cvt_pk_bf16_f32 v198, v4, v5
	v_cvt_pk_bf16_f32 v199, v6, v7
	global_store_dwordx4 v89, v[196:199], s[0:1] offset:0
	v_cvt_pk_bf16_f32 v200, v8, v9
	v_cvt_pk_bf16_f32 v201, v10, v11
	v_cvt_pk_bf16_f32 v202, v12, v13
	v_cvt_pk_bf16_f32 v203, v14, v15
	global_store_dwordx4 v89, v[200:203], s[0:1] offset:64
	s_add_u32 s0, s10, 0x40000
	s_addc_u32 s1, s11, 0
	v_cvt_pk_bf16_f32 v204, v16, v17
	v_cvt_pk_bf16_f32 v205, v18, v19
	v_cvt_pk_bf16_f32 v206, v20, v21
	v_cvt_pk_bf16_f32 v207, v22, v23
	global_store_dwordx4 v89, v[204:207], s[0:1] offset:0
	v_cvt_pk_bf16_f32 v208, v24, v25
	v_cvt_pk_bf16_f32 v209, v26, v27
	v_cvt_pk_bf16_f32 v210, v28, v29
	v_cvt_pk_bf16_f32 v211, v30, v31
	global_store_dwordx4 v89, v[208:211], s[0:1] offset:64
	s_add_u32 s0, s10, 0x80000
	s_addc_u32 s1, s11, 0
	v_cvt_pk_bf16_f32 v212, v32, v33
	v_cvt_pk_bf16_f32 v213, v34, v35
	v_cvt_pk_bf16_f32 v214, v36, v37
	v_cvt_pk_bf16_f32 v215, v38, v39
	global_store_dwordx4 v89, v[212:215], s[0:1] offset:0
	v_cvt_pk_bf16_f32 v216, v40, v41
	v_cvt_pk_bf16_f32 v217, v42, v43
	v_cvt_pk_bf16_f32 v218, v44, v45
	v_cvt_pk_bf16_f32 v219, v46, v47
	global_store_dwordx4 v89, v[216:219], s[0:1] offset:64
	s_add_u32 s0, s10, 0xc0000
	s_addc_u32 s1, s11, 0
	v_cvt_pk_bf16_f32 v220, v48, v49
	v_cvt_pk_bf16_f32 v221, v50, v51
	v_cvt_pk_bf16_f32 v222, v52, v53
	v_cvt_pk_bf16_f32 v223, v54, v55
	global_store_dwordx4 v89, v[220:223], s[0:1] offset:0
	v_cvt_pk_bf16_f32 v224, v56, v57
	v_cvt_pk_bf16_f32 v225, v58, v59
	v_cvt_pk_bf16_f32 v226, v60, v61
	v_cvt_pk_bf16_f32 v227, v62, v63
	global_store_dwordx4 v89, v[224:227], s[0:1] offset:64
	s_add_u32 s0, s12, 0x0
	s_addc_u32 s1, s13, 0
	v_cvt_pk_bf16_f32 v64, v94, v95
	v_cvt_pk_bf16_f32 v65, v96, v97
	v_cvt_pk_bf16_f32 v66, v98, v99
	v_cvt_pk_bf16_f32 v67, v100, v101
	global_store_dwordx4 v89, v[64:67], s[0:1] offset:0
	v_cvt_pk_bf16_f32 v68, v102, v103
	v_cvt_pk_bf16_f32 v69, v104, v105
	v_cvt_pk_bf16_f32 v70, v106, v107
	v_cvt_pk_bf16_f32 v71, v108, v109
	global_store_dwordx4 v89, v[68:71], s[0:1] offset:64
	s_add_u32 s0, s12, 0x40000
	s_addc_u32 s1, s13, 0
	v_cvt_pk_bf16_f32 v72, v110, v111
	v_cvt_pk_bf16_f32 v73, v112, v113
	v_cvt_pk_bf16_f32 v74, v114, v115
	v_cvt_pk_bf16_f32 v75, v116, v117
	global_store_dwordx4 v89, v[72:75], s[0:1] offset:0
	v_cvt_pk_bf16_f32 v76, v118, v119
	v_cvt_pk_bf16_f32 v77, v120, v121
	v_cvt_pk_bf16_f32 v78, v122, v123
	v_cvt_pk_bf16_f32 v79, v124, v125
	global_store_dwordx4 v89, v[76:79], s[0:1] offset:64
	s_add_u32 s0, s12, 0x80000
	s_addc_u32 s1, s13, 0
	v_cvt_pk_bf16_f32 v80, v126, v127
	v_cvt_pk_bf16_f32 v81, v128, v129
	v_cvt_pk_bf16_f32 v82, v130, v131
	v_cvt_pk_bf16_f32 v83, v132, v133
	global_store_dwordx4 v89, v[80:83], s[0:1] offset:0
	v_cvt_pk_bf16_f32 v84, v134, v135
	v_cvt_pk_bf16_f32 v85, v136, v137
	v_cvt_pk_bf16_f32 v86, v138, v139
	v_cvt_pk_bf16_f32 v87, v140, v141
	global_store_dwordx4 v89, v[84:87], s[0:1] offset:64
	s_add_u32 s0, s12, 0xc0000
	s_addc_u32 s1, s13, 0
	v_cvt_pk_bf16_f32 v158, v142, v143
	v_cvt_pk_bf16_f32 v159, v144, v145
	v_cvt_pk_bf16_f32 v160, v146, v147
	v_cvt_pk_bf16_f32 v161, v148, v149
	global_store_dwordx4 v89, v[158:161], s[0:1] offset:0
	v_cvt_pk_bf16_f32 v162, v150, v151
	v_cvt_pk_bf16_f32 v163, v152, v153
	v_cvt_pk_bf16_f32 v164, v154, v155
	v_cvt_pk_bf16_f32 v165, v156, v157
	global_store_dwordx4 v89, v[162:165], s[0:1] offset:64
	s_add_u32 s10, s10, 0x2000000
	s_addc_u32 s11, s11, 0
	s_add_u32 s12, s12, 0x2000000
	s_addc_u32 s13, s13, 0
	s_add_i32 s16, s16, -1
	s_cmp_lg_u32 s16, 0
	s_cbranch_scc1 .Lgio_tile
	s_waitcnt vmcnt(0)
	s_barrier
	s_branch .LBB0_428
